# scan helper waves, down-projection weight conversion items: the four LDS reads of each 16-byte output issued together (one lgkmcnt wait instead of four); on top of v74
# baseline (speedup 1.0000x reference)
.LBB0_1615:
	s_or_b64 exec, exec, s[30:31]
	s_movk_i32 s1, 0x104
	v_mul_lo_u32 v116, v148, s1
	v_readlane_b32 s2, v251, 59
	s_lshl_b32 s0, s0, 1
	s_nop 0
	v_add3_u32 v0, s2, v0, v116
	v_add_u32_e32 v116, 0x2e00, v0
	s_waitcnt vmcnt(0)
	ds_write2_b32 v116, v42, v43 offset1:1
	v_add_u32_e32 v42, 0x2e08, v0
	ds_write2_b32 v42, v44, v45 offset1:1
	v_add_u32_e32 v42, 0x3210, v0
	ds_write2_b32 v42, v46, v47 offset1:1
	v_add_u32_e32 v42, 0x3218, v0
	ds_write2_b32 v42, v48, v49 offset1:1
	v_add_u32_e32 v42, 0x3620, v0
	ds_write2_b32 v42, v54, v55 offset1:1
	v_add_u32_e32 v42, 0x3628, v0
	ds_write2_b32 v42, v56, v57 offset1:1
	v_add_u32_e32 v42, 0x3a30, v0
	ds_write2_b32 v42, v50, v51 offset1:1
	v_add_u32_e32 v42, 0x3a38, v0
	ds_write2_b32 v42, v52, v53 offset1:1
	v_add_u32_e32 v42, 0x3e40, v0
	ds_write2_b32 v42, v62, v63 offset1:1
	v_add_u32_e32 v42, 0x3e48, v0
	ds_write2_b32 v42, v64, v65 offset1:1
	v_add_u32_e32 v42, 0x4250, v0
	ds_write2_b32 v42, v58, v59 offset1:1
	v_add_u32_e32 v42, 0x4258, v0
	ds_write2_b32 v42, v60, v61 offset1:1
	v_add_u32_e32 v42, 0x4660, v0
	ds_write2_b32 v42, v70, v71 offset1:1
	v_add_u32_e32 v42, 0x4668, v0
	ds_write2_b32 v42, v72, v73 offset1:1
	v_add_u32_e32 v42, 0x4a70, v0
	ds_write2_b32 v42, v66, v67 offset1:1
	v_add_u32_e32 v42, 0x4a78, v0
	ds_write2_b32 v42, v68, v69 offset1:1
	v_add_u32_e32 v42, 0x4e80, v0
	ds_write2_b32 v42, v78, v79 offset1:1
	v_add_u32_e32 v42, 0x4e88, v0
	ds_write2_b32 v42, v80, v81 offset1:1
	v_add_u32_e32 v42, 0x5290, v0
	ds_write2_b32 v42, v74, v75 offset1:1
	v_add_u32_e32 v42, 0x5298, v0
	ds_write2_b32 v42, v76, v77 offset1:1
	v_add_u32_e32 v42, 0x56a0, v0
	ds_write2_b32 v42, v86, v87 offset1:1
	v_add_u32_e32 v42, 0x56a8, v0
	ds_write2_b32 v42, v88, v89 offset1:1
	v_add_u32_e32 v42, 0x5ab0, v0
	ds_write2_b32 v42, v82, v83 offset1:1
	v_add_u32_e32 v42, 0x5ab8, v0
	ds_write2_b32 v42, v84, v85 offset1:1
	v_add_u32_e32 v42, 0x5ec0, v0
	ds_write2_b32 v42, v94, v95 offset1:1
	v_add_u32_e32 v42, 0x5ec8, v0
	ds_write2_b32 v42, v96, v97 offset1:1
	v_add_u32_e32 v42, 0x62d0, v0
	ds_write2_b32 v42, v90, v91 offset1:1
	v_add_u32_e32 v42, 0x62d8, v0
	ds_write2_b32 v42, v92, v93 offset1:1
	v_add_u32_e32 v42, 0x66e0, v0
	ds_write2_b32 v42, v102, v103 offset1:1
	v_add_u32_e32 v42, 0x66e8, v0
	ds_write2_b32 v42, v104, v105 offset1:1
	v_add_u32_e32 v42, 0x6af0, v0
	v_add_u32_e32 v0, 0x6af8, v0
	ds_write2_b32 v0, v100, v101 offset1:1
	v_lshlrev_b32_e32 v0, 3, v115
	ds_write2_b32 v42, v98, v99 offset1:1
	v_and_b32_e32 v0, 56, v0
	v_mov_b32_e32 v42, s2
	v_mad_u32_u24 v45, v0, s1, v42
	v_readlane_b32 s1, v250, 30
	s_add_u32 s0, s1, s0
	v_readlane_b32 s1, v250, 36
	s_waitcnt lgkmcnt(0)
	v_ashrrev_i32_e32 v44, 3, v115
	s_addc_u32 s1, s1, 0
	v_lshlrev_b32_e32 v0, 1, v0
	v_lshl_add_u64 v[42:43], s[0:1], 0, v[0:1]
	v_add_u32_e32 v46, s24, v44
	s_movk_i32 s0, 0x800
	v_lshl_add_u32 v0, v44, 2, v45
	v_cmp_gt_i32_e32 vcc, s0, v46
	v_add_u32_e32 v45, 0x2c00, v0
	v_add_u32_e32 v44, 0x3000, v0
	v_add_u32_e32 v0, 0x3400, v0
	s_and_saveexec_b64 s[2:3], vcc
	s_cbranch_execz .LBB0_1617
	ds_read2_b32 v[232:233], v45 offset0:128 offset1:193
	ds_read2_b32 v[234:235], v44 offset0:2 offset1:67
	ds_read2_b32 v[236:237], v0 offset0:6 offset1:71
	ds_read2_b32 v[238:239], v44 offset0:132 offset1:197
	s_movk_i32 s0, 0x2c00
	s_waitcnt lgkmcnt(0)
	v_bfe_u32 v240, v233, 16, 1
	v_add3_u32 v240, v233, v240, s60
	v_bfe_u32 v241, v232, 16, 1
	v_add3_u32 v241, v232, v241, s60
	v_lshrrev_b32_e32 v241, 16, v241
	v_and_or_b32 v48, v240, s33, v241
	v_bfe_u32 v240, v235, 16, 1
	v_add3_u32 v240, v235, v240, s60
	v_bfe_u32 v241, v234, 16, 1
	v_add3_u32 v241, v234, v241, s60
	v_lshrrev_b32_e32 v241, 16, v241
	v_and_or_b32 v49, v240, s33, v241
	v_bfe_u32 v240, v239, 16, 1
	v_add3_u32 v240, v239, v240, s60
	v_bfe_u32 v241, v238, 16, 1
	v_add3_u32 v241, v238, v241, s60
	v_lshrrev_b32_e32 v241, 16, v241
	v_and_or_b32 v50, v240, s33, v241
	v_bfe_u32 v240, v237, 16, 1
	v_add3_u32 v240, v237, v240, s60
	v_bfe_u32 v241, v236, 16, 1
	v_add3_u32 v241, v236, v241, s60
	v_lshrrev_b32_e32 v241, 16, v241
	v_and_or_b32 v51, v240, s33, v241
	v_mad_i64_i32 v[52:53], s[0:1], v46, s0, v[42:43]
	global_store_dwordx4 v[52:53], v[48:51], off
.LBB0_1617:
	s_or_b64 exec, exec, s[2:3]
	v_add_u32_e32 v47, 8, v46
	s_movk_i32 s0, 0x800
	v_cmp_gt_i32_e32 vcc, s0, v47
	s_and_saveexec_b64 s[2:3], vcc
	s_cbranch_execz .LBB0_1619
	ds_read2_b32 v[232:233], v45 offset0:136 offset1:201
	ds_read2_b32 v[234:235], v44 offset0:10 offset1:75
	ds_read2_b32 v[236:237], v44 offset0:140 offset1:205
	ds_read2_b32 v[238:239], v0 offset0:14 offset1:79
	s_movk_i32 s0, 0x2c00
	s_waitcnt lgkmcnt(0)
	v_bfe_u32 v240, v233, 16, 1
	v_add3_u32 v240, v233, v240, s60
	v_bfe_u32 v241, v232, 16, 1
	v_add3_u32 v241, v232, v241, s60
	v_lshrrev_b32_e32 v241, 16, v241
	v_and_or_b32 v48, v240, s33, v241
	v_bfe_u32 v240, v235, 16, 1
	v_add3_u32 v240, v235, v240, s60
	v_bfe_u32 v241, v234, 16, 1
	v_add3_u32 v241, v234, v241, s60
	v_lshrrev_b32_e32 v241, 16, v241
	v_and_or_b32 v49, v240, s33, v241
	v_bfe_u32 v240, v237, 16, 1
	v_add3_u32 v240, v237, v240, s60
	v_bfe_u32 v241, v236, 16, 1
	v_add3_u32 v241, v236, v241, s60
	v_lshrrev_b32_e32 v241, 16, v241
	v_and_or_b32 v50, v240, s33, v241
	v_bfe_u32 v240, v239, 16, 1
	v_add3_u32 v240, v239, v240, s60
	v_bfe_u32 v241, v238, 16, 1
	v_add3_u32 v241, v238, v241, s60
	v_lshrrev_b32_e32 v241, 16, v241
	v_and_or_b32 v51, v240, s33, v241
	v_mad_i64_i32 v[52:53], s[0:1], v47, s0, v[42:43]
	global_store_dwordx4 v[52:53], v[48:51], off
.LBB0_1619:
	s_or_b64 exec, exec, s[2:3]
	v_add_u32_e32 v47, 16, v46
	s_movk_i32 s0, 0x800
	v_cmp_gt_i32_e32 vcc, s0, v47
	s_and_saveexec_b64 s[2:3], vcc
	s_cbranch_execz .LBB0_1621
	ds_read2_b32 v[232:233], v45 offset0:144 offset1:209
	ds_read2_b32 v[234:235], v44 offset0:18 offset1:83
	ds_read2_b32 v[236:237], v44 offset0:148 offset1:213
	ds_read2_b32 v[238:239], v0 offset0:22 offset1:87
	s_movk_i32 s0, 0x2c00
	s_waitcnt lgkmcnt(0)
	v_bfe_u32 v240, v233, 16, 1
	v_add3_u32 v240, v233, v240, s60
	v_bfe_u32 v241, v232, 16, 1
	v_add3_u32 v241, v232, v241, s60
	v_lshrrev_b32_e32 v241, 16, v241
	v_and_or_b32 v48, v240, s33, v241
	v_bfe_u32 v240, v235, 16, 1
	v_add3_u32 v240, v235, v240, s60
	v_bfe_u32 v241, v234, 16, 1
	v_add3_u32 v241, v234, v241, s60
	v_lshrrev_b32_e32 v241, 16, v241
	v_and_or_b32 v49, v240, s33, v241
	v_bfe_u32 v240, v237, 16, 1
	v_add3_u32 v240, v237, v240, s60
	v_bfe_u32 v241, v236, 16, 1
	v_add3_u32 v241, v236, v241, s60
	v_lshrrev_b32_e32 v241, 16, v241
	v_and_or_b32 v50, v240, s33, v241
	v_bfe_u32 v240, v239, 16, 1
	v_add3_u32 v240, v239, v240, s60
	v_bfe_u32 v241, v238, 16, 1
	v_add3_u32 v241, v238, v241, s60
	v_lshrrev_b32_e32 v241, 16, v241
	v_and_or_b32 v51, v240, s33, v241
	v_mad_i64_i32 v[52:53], s[0:1], v47, s0, v[42:43]
	global_store_dwordx4 v[52:53], v[48:51], off
.LBB0_1621:
	s_or_b64 exec, exec, s[2:3]
	v_add_u32_e32 v47, 24, v46
	s_movk_i32 s0, 0x800
	v_cmp_gt_i32_e32 vcc, s0, v47
	s_and_saveexec_b64 s[2:3], vcc
	s_cbranch_execz .LBB0_1623
	ds_read2_b32 v[232:233], v45 offset0:152 offset1:217
	ds_read2_b32 v[234:235], v44 offset0:26 offset1:91
	ds_read2_b32 v[236:237], v44 offset0:156 offset1:221
	ds_read2_b32 v[238:239], v0 offset0:30 offset1:95
	s_movk_i32 s0, 0x2c00
	s_waitcnt lgkmcnt(0)
	v_bfe_u32 v240, v233, 16, 1
	v_add3_u32 v240, v233, v240, s60
	v_bfe_u32 v241, v232, 16, 1
	v_add3_u32 v241, v232, v241, s60
	v_lshrrev_b32_e32 v241, 16, v241
	v_and_or_b32 v48, v240, s33, v241
	v_bfe_u32 v240, v235, 16, 1
	v_add3_u32 v240, v235, v240, s60
	v_bfe_u32 v241, v234, 16, 1
	v_add3_u32 v241, v234, v241, s60
	v_lshrrev_b32_e32 v241, 16, v241
	v_and_or_b32 v49, v240, s33, v241
	v_bfe_u32 v240, v237, 16, 1
	v_add3_u32 v240, v237, v240, s60
	v_bfe_u32 v241, v236, 16, 1
	v_add3_u32 v241, v236, v241, s60
	v_lshrrev_b32_e32 v241, 16, v241
	v_and_or_b32 v50, v240, s33, v241
	v_bfe_u32 v240, v239, 16, 1
	v_add3_u32 v240, v239, v240, s60
	v_bfe_u32 v241, v238, 16, 1
	v_add3_u32 v241, v238, v241, s60
	v_lshrrev_b32_e32 v241, 16, v241
	v_and_or_b32 v51, v240, s33, v241
	v_mad_i64_i32 v[52:53], s[0:1], v47, s0, v[42:43]
	global_store_dwordx4 v[52:53], v[48:51], off
.LBB0_1623:
	s_or_b64 exec, exec, s[2:3]
	v_add_u32_e32 v47, 32, v46
	s_movk_i32 s0, 0x800
	v_cmp_gt_i32_e32 vcc, s0, v47
	s_and_saveexec_b64 s[2:3], vcc
	s_cbranch_execz .LBB0_1625
	ds_read2_b32 v[232:233], v45 offset0:160 offset1:225
	ds_read2_b32 v[234:235], v44 offset0:34 offset1:99
	ds_read2_b32 v[236:237], v44 offset0:164 offset1:229
	ds_read2_b32 v[238:239], v0 offset0:38 offset1:103
	s_movk_i32 s0, 0x2c00
	s_waitcnt lgkmcnt(0)
	v_bfe_u32 v240, v233, 16, 1
	v_add3_u32 v240, v233, v240, s60
	v_bfe_u32 v241, v232, 16, 1
	v_add3_u32 v241, v232, v241, s60
	v_lshrrev_b32_e32 v241, 16, v241
	v_and_or_b32 v48, v240, s33, v241
	v_bfe_u32 v240, v235, 16, 1
	v_add3_u32 v240, v235, v240, s60
	v_bfe_u32 v241, v234, 16, 1
	v_add3_u32 v241, v234, v241, s60
	v_lshrrev_b32_e32 v241, 16, v241
	v_and_or_b32 v49, v240, s33, v241
	v_bfe_u32 v240, v237, 16, 1
	v_add3_u32 v240, v237, v240, s60
	v_bfe_u32 v241, v236, 16, 1
	v_add3_u32 v241, v236, v241, s60
	v_lshrrev_b32_e32 v241, 16, v241
	v_and_or_b32 v50, v240, s33, v241
	v_bfe_u32 v240, v239, 16, 1
	v_add3_u32 v240, v239, v240, s60
	v_bfe_u32 v241, v238, 16, 1
	v_add3_u32 v241, v238, v241, s60
	v_lshrrev_b32_e32 v241, 16, v241
	v_and_or_b32 v51, v240, s33, v241
	v_mad_i64_i32 v[52:53], s[0:1], v47, s0, v[42:43]
	global_store_dwordx4 v[52:53], v[48:51], off
.LBB0_1625:
	s_or_b64 exec, exec, s[2:3]
	v_add_u32_e32 v47, 40, v46
	s_movk_i32 s0, 0x800
	v_cmp_gt_i32_e32 vcc, s0, v47
	s_and_saveexec_b64 s[2:3], vcc
	s_cbranch_execz .LBB0_1627
	ds_read2_b32 v[232:233], v45 offset0:168 offset1:233
	ds_read2_b32 v[234:235], v44 offset0:42 offset1:107
	ds_read2_b32 v[236:237], v44 offset0:172 offset1:237
	ds_read2_b32 v[238:239], v0 offset0:46 offset1:111
	s_movk_i32 s0, 0x2c00
	s_waitcnt lgkmcnt(0)
	v_bfe_u32 v240, v233, 16, 1
	v_add3_u32 v240, v233, v240, s60
	v_bfe_u32 v241, v232, 16, 1
	v_add3_u32 v241, v232, v241, s60
	v_lshrrev_b32_e32 v241, 16, v241
	v_and_or_b32 v48, v240, s33, v241
	v_bfe_u32 v240, v235, 16, 1
	v_add3_u32 v240, v235, v240, s60
	v_bfe_u32 v241, v234, 16, 1
	v_add3_u32 v241, v234, v241, s60
	v_lshrrev_b32_e32 v241, 16, v241
	v_and_or_b32 v49, v240, s33, v241
	v_bfe_u32 v240, v237, 16, 1
	v_add3_u32 v240, v237, v240, s60
	v_bfe_u32 v241, v236, 16, 1
	v_add3_u32 v241, v236, v241, s60
	v_lshrrev_b32_e32 v241, 16, v241
	v_and_or_b32 v50, v240, s33, v241
	v_bfe_u32 v240, v239, 16, 1
	v_add3_u32 v240, v239, v240, s60
	v_bfe_u32 v241, v238, 16, 1
	v_add3_u32 v241, v238, v241, s60
	v_lshrrev_b32_e32 v241, 16, v241
	v_and_or_b32 v51, v240, s33, v241
	v_mad_i64_i32 v[52:53], s[0:1], v47, s0, v[42:43]
	global_store_dwordx4 v[52:53], v[48:51], off
.LBB0_1627:
	s_or_b64 exec, exec, s[2:3]
	v_add_u32_e32 v47, 48, v46
	s_movk_i32 s0, 0x800
	v_cmp_gt_i32_e32 vcc, s0, v47
	s_and_saveexec_b64 s[2:3], vcc
	s_cbranch_execz .LBB0_1629
	ds_read2_b32 v[232:233], v45 offset0:176 offset1:241
	ds_read2_b32 v[234:235], v44 offset0:50 offset1:115
	ds_read2_b32 v[236:237], v44 offset0:180 offset1:245
	ds_read2_b32 v[238:239], v0 offset0:54 offset1:119
	s_movk_i32 s0, 0x2c00
	s_waitcnt lgkmcnt(0)
	v_bfe_u32 v240, v233, 16, 1
	v_add3_u32 v240, v233, v240, s60
	v_bfe_u32 v241, v232, 16, 1
	v_add3_u32 v241, v232, v241, s60
	v_lshrrev_b32_e32 v241, 16, v241
	v_and_or_b32 v48, v240, s33, v241
	v_bfe_u32 v240, v235, 16, 1
	v_add3_u32 v240, v235, v240, s60
	v_bfe_u32 v241, v234, 16, 1
	v_add3_u32 v241, v234, v241, s60
	v_lshrrev_b32_e32 v241, 16, v241
	v_and_or_b32 v49, v240, s33, v241
	v_bfe_u32 v240, v237, 16, 1
	v_add3_u32 v240, v237, v240, s60
	v_bfe_u32 v241, v236, 16, 1
	v_add3_u32 v241, v236, v241, s60
	v_lshrrev_b32_e32 v241, 16, v241
	v_and_or_b32 v50, v240, s33, v241
	v_bfe_u32 v240, v239, 16, 1
	v_add3_u32 v240, v239, v240, s60
	v_bfe_u32 v241, v238, 16, 1
	v_add3_u32 v241, v238, v241, s60
	v_lshrrev_b32_e32 v241, 16, v241
	v_and_or_b32 v51, v240, s33, v241
	v_mad_i64_i32 v[52:53], s[0:1], v47, s0, v[42:43]
	global_store_dwordx4 v[52:53], v[48:51], off
.LBB0_1629:
	s_or_b64 exec, exec, s[2:3]
	v_add_u32_e32 v46, 56, v46
	s_movk_i32 s0, 0x800
	v_cmp_gt_i32_e32 vcc, s0, v46
	s_and_saveexec_b64 s[2:3], vcc
	s_cbranch_execz .LBB0_1631
	ds_read2_b32 v[232:233], v45 offset0:184 offset1:249
	ds_read2_b32 v[234:235], v44 offset0:58 offset1:123
	ds_read2_b32 v[236:237], v44 offset0:188 offset1:253
	ds_read2_b32 v[238:239], v0 offset0:62 offset1:127
	s_movk_i32 s0, 0x2c00
	s_waitcnt lgkmcnt(0)
	v_bfe_u32 v240, v233, 16, 1
	v_add3_u32 v240, v233, v240, s60
	v_bfe_u32 v241, v232, 16, 1
	v_add3_u32 v241, v232, v241, s60
	v_lshrrev_b32_e32 v241, 16, v241
	v_and_or_b32 v48, v240, s33, v241
	v_bfe_u32 v240, v235, 16, 1
	v_add3_u32 v240, v235, v240, s60
	v_bfe_u32 v241, v234, 16, 1
	v_add3_u32 v241, v234, v241, s60
	v_lshrrev_b32_e32 v241, 16, v241
	v_and_or_b32 v49, v240, s33, v241
	v_bfe_u32 v240, v237, 16, 1
	v_add3_u32 v240, v237, v240, s60
	v_bfe_u32 v241, v236, 16, 1
	v_add3_u32 v241, v236, v241, s60
	v_lshrrev_b32_e32 v241, 16, v241
	v_and_or_b32 v50, v240, s33, v241
	v_bfe_u32 v240, v239, 16, 1
	v_add3_u32 v240, v239, v240, s60
	v_bfe_u32 v241, v238, 16, 1
	v_add3_u32 v241, v238, v241, s60
	v_lshrrev_b32_e32 v241, 16, v241
	v_and_or_b32 v51, v240, s33, v241
	v_mad_i64_i32 v[42:43], s[0:1], v46, s0, v[42:43]
	global_store_dwordx4 v[42:43], v[48:51], off
